# plus: rope cos/sin rows of the q/k epilogue requested ahead (steps 1-5 with step 0, steps 6-7 at step 3) instead of one dependent load pair per step
# speedup vs baseline: 1.0041x; 1.0017x over previous
;     __device__ __forceinline__ void operator()(const f32x4 (&acc)[2][2][4][2], const Unit& u, int wr, int wc, int fr, int fq) const {
;     ...
;             for (int ai = 0; ai < 2; ++ai)
; #pragma unroll
;                 for (int m = 0; m < 4; ++m) {
;                     const int row = rbase + ai * HALF + m * 16, tt = wr * 64 + m * 16 + fr, cc = ccb + ai;
;                     f32x4 cs = {1.f, 1.f, 1.f, 1.f}, sn = {0.f, 0.f, 0.f, 0.f};
;                     if (!ctx) { const int t = row & (SEQ - 1); cs = *(const f32x4*)(rope + t * 64 + d0); sn = *(const f32x4*)(rope + SEQ * 64 + t * 64 + d0); }
.LBB0_143:
	s_andn2_b64 vcc, exec, s[0:1]
	s_cbranch_vccnz .LBB0_129
	s_waitcnt lgkmcnt(0)
	s_add_u32 s26, s24, 0x12eb4000
	v_cndmask_b32_e64 v0, 0, 1, s[6:7]
	s_addc_u32 s27, s25, 0
	v_cmp_ne_u32_e64 s[4:5], 1, v0
	s_andn2_b64 vcc, exec, s[6:7]
	v_lshlrev_b32_e32 v156, 2, v146
	s_cbranch_vccnz .LBB0_146
	v_lshlrev_b32_e32 v0, 8, v154
	v_and_b32_e32 v0, 0x7cf00, v0
	v_mov_b32_e32 v157, v1
	v_lshl_add_u64 v[132:133], s[24:25], 0, v[0:1]
	v_lshl_add_u64 v[132:133], v[132:133], 0, v[156:157]
	v_lshl_add_u64 v[130:131], s[26:27], 0, v[0:1]
	v_add_co_u32_e32 v134, vcc, 0x12f34000, v132
	v_lshl_add_u64 v[130:131], v[130:131], 0, v[156:157]
	s_nop 0
	v_addc_co_u32_e32 v135, vcc, 0, v133, vcc
	v_mov_b32_e32 v210, v130
	v_mov_b32_e32 v211, v131
	v_mov_b32_e32 v212, v134
	v_mov_b32_e32 v213, v135
	s_mov_b64 s[100:101], 0x1000
	v_lshl_add_u64 v[214:215], v[210:211], 0, s[100:101]
	v_lshl_add_u64 v[244:245], v[212:213], 0, s[100:101]
	global_load_dwordx4 v[190:193], v[214:215], off
	global_load_dwordx4 v[194:197], v[244:245], off
	s_mov_b64 s[100:101], 0x2000
	v_lshl_add_u64 v[214:215], v[210:211], 0, s[100:101]
	v_lshl_add_u64 v[244:245], v[212:213], 0, s[100:101]
	global_load_dwordx4 v[198:201], v[214:215], off
	global_load_dwordx4 v[202:205], v[244:245], off
	s_mov_b64 s[100:101], 0x3000
	v_lshl_add_u64 v[214:215], v[210:211], 0, s[100:101]
	v_lshl_add_u64 v[244:245], v[212:213], 0, s[100:101]
	global_load_dwordx4 v[206:209], v[214:215], off
	global_load_dwordx4 v[224:227], v[244:245], off
	s_mov_b64 s[100:101], 0x8000
	v_lshl_add_u64 v[214:215], v[210:211], 0, s[100:101]
	v_lshl_add_u64 v[244:245], v[212:213], 0, s[100:101]
	global_load_dwordx4 v[228:231], v[214:215], off
	global_load_dwordx4 v[232:235], v[244:245], off
	s_mov_b64 s[100:101], 0x9000
	v_lshl_add_u64 v[214:215], v[210:211], 0, s[100:101]
	v_lshl_add_u64 v[244:245], v[212:213], 0, s[100:101]
	global_load_dwordx4 v[236:239], v[214:215], off
	global_load_dwordx4 v[240:243], v[244:245], off
	global_load_dwordx4 v[130:133], v[130:131], off
	s_nop 0
	global_load_dwordx4 v[134:137], v[134:135], off
	s_branch .LBB0_147

;     __device__ __forceinline__ void operator()(const f32x4 (&acc)[2][2][4][2], const Unit& u, int wr, int wc, int fr, int fq) const {
;     ...
;                     const int row = rbase + ai * HALF + m * 16, tt = wr * 64 + m * 16 + fr, cc = ccb + ai;
;                     f32x4 cs = {1.f, 1.f, 1.f, 1.f}, sn = {0.f, 0.f, 0.f, 0.f};
;                     if (!ctx) { const int t = row & (SEQ - 1); cs = *(const f32x4*)(rope + t * 64 + d0); sn = *(const f32x4*)(rope + SEQ * 64 + t * 64 + d0); }
.LBB0_154:
	v_lshlrev_b32_e32 v114, 8, v124
	v_and_b32_e32 v114, 0x7df00, v114
	v_mov_b32_e32 v115, v1
	v_lshl_add_u64 v[116:117], s[26:27], 0, v[114:115]
	v_mov_b32_e32 v157, v1
	v_lshl_add_u64 v[114:115], s[24:25], 0, v[114:115]
	v_lshl_add_u64 v[114:115], v[114:115], 0, v[156:157]
	v_add_co_u32_e32 v118, vcc, 0x12f34000, v114
	v_lshl_add_u64 v[116:117], v[116:117], 0, v[156:157]
	s_nop 0
	v_addc_co_u32_e32 v119, vcc, 0, v115, vcc
	s_waitcnt vmcnt(0)
	v_mov_b32_e32 v114, v190
	v_mov_b32_e32 v115, v191
	v_mov_b32_e32 v116, v192
	v_mov_b32_e32 v117, v193
	v_mov_b32_e32 v118, v194
	v_mov_b32_e32 v119, v195
	v_mov_b32_e32 v120, v196
	v_mov_b32_e32 v121, v197
	s_branch .LBB0_158

;     __device__ __forceinline__ void operator()(const f32x4 (&acc)[2][2][4][2], const Unit& u, int wr, int wc, int fr, int fq) const {
;     ...
;                     const int row = rbase + ai * HALF + m * 16, tt = wr * 64 + m * 16 + fr, cc = ccb + ai;
;                     f32x4 cs = {1.f, 1.f, 1.f, 1.f}, sn = {0.f, 0.f, 0.f, 0.f};
;                     if (!ctx) { const int t = row & (SEQ - 1); cs = *(const f32x4*)(rope + t * 64 + d0); sn = *(const f32x4*)(rope + SEQ * 64 + t * 64 + d0); }
.LBB0_165:
	v_lshlrev_b32_e32 v98, 8, v106
	v_and_b32_e32 v98, 0x7ef00, v98
	v_mov_b32_e32 v99, v1
	v_lshl_add_u64 v[100:101], s[26:27], 0, v[98:99]
	v_mov_b32_e32 v157, v1
	v_lshl_add_u64 v[98:99], s[24:25], 0, v[98:99]
	v_lshl_add_u64 v[98:99], v[98:99], 0, v[156:157]
	v_add_co_u32_e32 v102, vcc, 0x12f34000, v98
	v_lshl_add_u64 v[100:101], v[100:101], 0, v[156:157]
	s_nop 0
	v_addc_co_u32_e32 v103, vcc, 0, v99, vcc
	s_waitcnt vmcnt(0)
	v_mov_b32_e32 v98, v198
	v_mov_b32_e32 v99, v199
	v_mov_b32_e32 v100, v200
	v_mov_b32_e32 v101, v201
	v_mov_b32_e32 v102, v202
	v_mov_b32_e32 v103, v203
	v_mov_b32_e32 v104, v204
	v_mov_b32_e32 v105, v205
	s_branch .LBB0_169

;     __device__ __forceinline__ void operator()(const f32x4 (&acc)[2][2][4][2], const Unit& u, int wr, int wc, int fr, int fq) const {
;     ...
;                     const int row = rbase + ai * HALF + m * 16, tt = wr * 64 + m * 16 + fr, cc = ccb + ai;
;                     f32x4 cs = {1.f, 1.f, 1.f, 1.f}, sn = {0.f, 0.f, 0.f, 0.f};
;                     if (!ctx) { const int t = row & (SEQ - 1); cs = *(const f32x4*)(rope + t * 64 + d0); sn = *(const f32x4*)(rope + SEQ * 64 + t * 64 + d0); }
.LBB0_176:
	v_lshlrev_b32_e32 v82, 8, v90
	v_and_b32_e32 v82, 0x7ff00, v82
	v_mov_b32_e32 v83, v1
	v_lshl_add_u64 v[84:85], s[26:27], 0, v[82:83]
	v_mov_b32_e32 v157, v1
	v_lshl_add_u64 v[82:83], s[24:25], 0, v[82:83]
	v_lshl_add_u64 v[82:83], v[82:83], 0, v[156:157]
	v_add_co_u32_e32 v86, vcc, 0x12f34000, v82
	v_lshl_add_u64 v[84:85], v[84:85], 0, v[156:157]
	s_nop 0
	v_addc_co_u32_e32 v87, vcc, 0, v83, vcc
	s_waitcnt vmcnt(0)
	v_mov_b32_e32 v82, v206
	v_mov_b32_e32 v83, v207
	v_mov_b32_e32 v84, v208
	v_mov_b32_e32 v85, v209
	v_mov_b32_e32 v86, v224
	v_mov_b32_e32 v87, v225
	v_mov_b32_e32 v88, v226
	v_mov_b32_e32 v89, v227
	s_mov_b64 s[100:101], 0xa000
	v_lshl_add_u64 v[214:215], v[210:211], 0, s[100:101]
	v_lshl_add_u64 v[244:245], v[212:213], 0, s[100:101]
	global_load_dwordx4 v[190:193], v[214:215], off
	global_load_dwordx4 v[194:197], v[244:245], off
	s_mov_b64 s[100:101], 0xb000
	v_lshl_add_u64 v[214:215], v[210:211], 0, s[100:101]
	v_lshl_add_u64 v[244:245], v[212:213], 0, s[100:101]
	global_load_dwordx4 v[198:201], v[214:215], off
	global_load_dwordx4 v[202:205], v[244:245], off
	s_branch .LBB0_180

;     __device__ __forceinline__ void operator()(const f32x4 (&acc)[2][2][4][2], const Unit& u, int wr, int wc, int fr, int fq) const {
;     ...
;                     const int row = rbase + ai * HALF + m * 16, tt = wr * 64 + m * 16 + fr, cc = ccb + ai;
;                     f32x4 cs = {1.f, 1.f, 1.f, 1.f}, sn = {0.f, 0.f, 0.f, 0.f};
;                     if (!ctx) { const int t = row & (SEQ - 1); cs = *(const f32x4*)(rope + t * 64 + d0); sn = *(const f32x4*)(rope + SEQ * 64 + t * 64 + d0); }
.LBB0_187:
	v_lshlrev_b32_e32 v66, 8, v74
	v_and_b32_e32 v66, 0x7cf00, v66
	v_mov_b32_e32 v67, v1
	v_lshl_add_u64 v[68:69], s[26:27], 0, v[66:67]
	v_mov_b32_e32 v157, v1
	v_lshl_add_u64 v[66:67], s[24:25], 0, v[66:67]
	v_lshl_add_u64 v[66:67], v[66:67], 0, v[156:157]
	v_add_co_u32_e32 v70, vcc, 0x12f34000, v66
	v_lshl_add_u64 v[68:69], v[68:69], 0, v[156:157]
	s_nop 0
	v_addc_co_u32_e32 v71, vcc, 0, v67, vcc
	s_waitcnt vmcnt(0)
	v_mov_b32_e32 v66, v228
	v_mov_b32_e32 v67, v229
	v_mov_b32_e32 v68, v230
	v_mov_b32_e32 v69, v231
	v_mov_b32_e32 v70, v232
	v_mov_b32_e32 v71, v233
	v_mov_b32_e32 v72, v234
	v_mov_b32_e32 v73, v235
	s_branch .LBB0_191

;     __device__ __forceinline__ void operator()(const f32x4 (&acc)[2][2][4][2], const Unit& u, int wr, int wc, int fr, int fq) const {
;     ...
;                     const int row = rbase + ai * HALF + m * 16, tt = wr * 64 + m * 16 + fr, cc = ccb + ai;
;                     f32x4 cs = {1.f, 1.f, 1.f, 1.f}, sn = {0.f, 0.f, 0.f, 0.f};
;                     if (!ctx) { const int t = row & (SEQ - 1); cs = *(const f32x4*)(rope + t * 64 + d0); sn = *(const f32x4*)(rope + SEQ * 64 + t * 64 + d0); }
.LBB0_198:
	v_lshlrev_b32_e32 v50, 8, v58
	v_and_b32_e32 v50, 0x7df00, v50
	v_mov_b32_e32 v51, v1
	v_lshl_add_u64 v[52:53], s[26:27], 0, v[50:51]
	v_mov_b32_e32 v157, v1
	v_lshl_add_u64 v[50:51], s[24:25], 0, v[50:51]
	v_lshl_add_u64 v[50:51], v[50:51], 0, v[156:157]
	v_add_co_u32_e32 v54, vcc, 0x12f34000, v50
	v_lshl_add_u64 v[52:53], v[52:53], 0, v[156:157]
	s_nop 0
	v_addc_co_u32_e32 v55, vcc, 0, v51, vcc
	s_waitcnt vmcnt(0)
	v_mov_b32_e32 v50, v236
	v_mov_b32_e32 v51, v237
	v_mov_b32_e32 v52, v238
	v_mov_b32_e32 v53, v239
	v_mov_b32_e32 v54, v240
	v_mov_b32_e32 v55, v241
	v_mov_b32_e32 v56, v242
	v_mov_b32_e32 v57, v243
	s_branch .LBB0_202

;     __device__ __forceinline__ void operator()(const f32x4 (&acc)[2][2][4][2], const Unit& u, int wr, int wc, int fr, int fq) const {
;     ...
;                     const int row = rbase + ai * HALF + m * 16, tt = wr * 64 + m * 16 + fr, cc = ccb + ai;
;                     f32x4 cs = {1.f, 1.f, 1.f, 1.f}, sn = {0.f, 0.f, 0.f, 0.f};
;                     if (!ctx) { const int t = row & (SEQ - 1); cs = *(const f32x4*)(rope + t * 64 + d0); sn = *(const f32x4*)(rope + SEQ * 64 + t * 64 + d0); }
.LBB0_209:
	v_lshlrev_b32_e32 v34, 8, v42
	v_and_b32_e32 v34, 0x7ef00, v34
	v_mov_b32_e32 v35, v1
	v_lshl_add_u64 v[36:37], s[26:27], 0, v[34:35]
	v_mov_b32_e32 v157, v1
	v_lshl_add_u64 v[34:35], s[24:25], 0, v[34:35]
	v_lshl_add_u64 v[34:35], v[34:35], 0, v[156:157]
	v_add_co_u32_e32 v38, vcc, 0x12f34000, v34
	v_lshl_add_u64 v[36:37], v[36:37], 0, v[156:157]
	s_nop 0
	v_addc_co_u32_e32 v39, vcc, 0, v35, vcc
	s_waitcnt vmcnt(0)
	v_mov_b32_e32 v34, v190
	v_mov_b32_e32 v35, v191
	v_mov_b32_e32 v36, v192
	v_mov_b32_e32 v37, v193
	v_mov_b32_e32 v38, v194
	v_mov_b32_e32 v39, v195
	v_mov_b32_e32 v40, v196
	v_mov_b32_e32 v41, v197
	s_branch .LBB0_213

;     __device__ __forceinline__ void operator()(const f32x4 (&acc)[2][2][4][2], const Unit& u, int wr, int wc, int fr, int fq) const {
;     ...
;                     const int row = rbase + ai * HALF + m * 16, tt = wr * 64 + m * 16 + fr, cc = ccb + ai;
;                     f32x4 cs = {1.f, 1.f, 1.f, 1.f}, sn = {0.f, 0.f, 0.f, 0.f};
;                     if (!ctx) { const int t = row & (SEQ - 1); cs = *(const f32x4*)(rope + t * 64 + d0); sn = *(const f32x4*)(rope + SEQ * 64 + t * 64 + d0); }
.LBB0_220:
	v_lshlrev_b32_e32 v18, 8, v26
	v_and_b32_e32 v18, 0x7ff00, v18
	v_mov_b32_e32 v19, v1
	v_lshl_add_u64 v[20:21], s[26:27], 0, v[18:19]
	v_mov_b32_e32 v157, v1
	v_lshl_add_u64 v[18:19], s[24:25], 0, v[18:19]
	v_lshl_add_u64 v[18:19], v[18:19], 0, v[156:157]
	v_add_co_u32_e32 v22, vcc, 0x12f34000, v18
	v_lshl_add_u64 v[20:21], v[20:21], 0, v[156:157]
	s_nop 0
	v_addc_co_u32_e32 v23, vcc, 0, v19, vcc
	s_waitcnt vmcnt(0)
	v_mov_b32_e32 v18, v198
	v_mov_b32_e32 v19, v199
	v_mov_b32_e32 v20, v200
	v_mov_b32_e32 v21, v201
	v_mov_b32_e32 v22, v202
	v_mov_b32_e32 v23, v203
	v_mov_b32_e32 v24, v204
	v_mov_b32_e32 v25, v205
	s_branch .LBB0_224
